# attention row-max chains rebuilt (older QK accumulator first, no s_nop padding, 2 fewer ops)
# speedup vs baseline: 1.0012x; 1.0012x over previous
.LBB0_644:
	v_add_u32_e32 v181, s44, v203
	v_lshl_add_u64 v[186:187], v[184:185], 0, s[42:43]
	v_lshl_add_u64 v[110:111], v[186:187], 0, s[76:77]
	s_add_i32 s44, s70, s35
	s_mov_b32 m0, s44
	s_nop 0
	global_load_lds_dwordx4 v[110:111], off
	v_lshl_add_u64 v[188:189], v[182:183], 0, s[42:43]
	s_mov_b64 s[44:45], 0x15204000
	v_lshl_add_u64 v[110:111], v[188:189], 0, s[44:45]
	s_add_i32 s44, s68, s49
	s_mov_b32 m0, s44
	s_nop 0
	global_load_lds_dwordx4 v[110:111], off
	ds_read_b64_tr_b16 v[176:177], v181 offset:24576
	ds_read_b64_tr_b16 v[178:179], v181 offset:25088
	v_mfma_f32_32x32x16_bf16 v[96:111], v[172:175], v[140:143], v[32:47]
	v_add_f32_e32 v80, v64, v65
	v_add_f32_e32 v80, v66, v80
	v_add_f32_e32 v80, v67, v80
	v_add_f32_e32 v80, v68, v80
	v_add_f32_e32 v80, v69, v80
	v_cvt_pk_bf16_f32 v136, v64, v65
	v_cvt_pk_bf16_f32 v137, v66, v67
	ds_read_b64_tr_b16 v[172:173], v181 offset:28672
	ds_read_b64_tr_b16 v[174:175], v181 offset:29184
	v_add_f32_e32 v64, v70, v80
	v_mfma_f32_32x32x16_bf16 v[80:95], v[168:171], v[140:143], v[32:47]
	v_add_f32_e32 v64, v71, v64
	v_add_f32_e32 v64, v72, v64
	v_add_f32_e32 v116, v73, v64
	v_cvt_pk_bf16_f32 v138, v68, v69
	v_cvt_pk_bf16_f32 v139, v70, v71
	ds_read_b64_tr_b16 v[64:65], v181 offset:25600
	ds_read_b64_tr_b16 v[66:67], v181 offset:26112
	v_mfma_f32_32x32x16_bf16 v[96:111], v[164:167], v[132:135], v[96:111]
	v_add_f32_e32 v68, v74, v116
	v_add_f32_e32 v68, v75, v68
	v_add_f32_e32 v68, v76, v68
	v_add_f32_e32 v116, v77, v68
	v_cvt_pk_bf16_f32 v128, v72, v73
	v_cvt_pk_bf16_f32 v129, v74, v75
	ds_read_b64_tr_b16 v[68:69], v181 offset:29696
	ds_read_b64_tr_b16 v[70:71], v181 offset:30208
	v_mfma_f32_32x32x16_bf16 v[80:95], v[160:163], v[132:135], v[80:95]
	v_add_f32_e32 v72, v78, v116
	v_add_f32_e32 v72, v79, v72
	v_add_f32_e32 v72, v48, v72
	v_add_f32_e32 v116, v49, v72
	v_cvt_pk_bf16_f32 v130, v76, v77
	v_cvt_pk_bf16_f32 v131, v78, v79
	ds_read_b64_tr_b16 v[72:73], v181 offset:26624
	ds_read_b64_tr_b16 v[74:75], v181 offset:27136
	v_mfma_f32_32x32x16_bf16 v[96:111], v[156:159], v[120:123], v[96:111]
	v_add_f32_e32 v76, v50, v116
	v_add_f32_e32 v76, v51, v76
	v_add_f32_e32 v76, v52, v76
	v_add_f32_e32 v76, v53, v76
	v_cvt_pk_bf16_f32 v124, v48, v49
	v_cvt_pk_bf16_f32 v125, v50, v51
	ds_read_b64_tr_b16 v[48:49], v181 offset:30720
	ds_read_b64_tr_b16 v[50:51], v181 offset:31232
	v_mfma_f32_32x32x16_bf16 v[80:95], v[152:155], v[120:123], v[80:95]
	v_add_f32_e32 v76, v54, v76
	v_add_f32_e32 v76, v55, v76
	v_add_f32_e32 v76, v56, v76
	v_add_f32_e32 v76, v57, v76
	v_cvt_pk_bf16_f32 v126, v52, v53
	v_cvt_pk_bf16_f32 v127, v54, v55
	ds_read_b64_tr_b16 v[52:53], v181 offset:27648
	ds_read_b64_tr_b16 v[54:55], v181 offset:28160
	v_mfma_f32_32x32x16_bf16 v[96:111], v[148:151], v[112:115], v[96:111]
	v_add_f32_e32 v76, v58, v76
	v_add_f32_e32 v76, v59, v76
	v_add_f32_e32 v76, v60, v76
	v_add_f32_e32 v76, v61, v76
	v_cvt_pk_bf16_f32 v116, v56, v57
	v_cvt_pk_bf16_f32 v117, v58, v59
	ds_read_b64_tr_b16 v[56:57], v181 offset:31744
	ds_read_b64_tr_b16 v[58:59], v181 offset:32256
	v_mfma_f32_32x32x16_bf16 v[80:95], v[144:147], v[112:115], v[80:95]
	v_add_f32_e32 v76, v62, v76
	v_add_f32_e32 v76, v63, v76
	v_cvt_pk_bf16_f32 v118, v60, v61
	v_cvt_pk_bf16_f32 v119, v62, v63
	v_add_f32_e32 v191, v192, v76
	v_max_f32_e32 v60, v96, v97
	v_max3_f32 v61, v98, v99, v100
	v_max3_f32 v60, v60, v102, v103
	v_max3_f32 v61, v61, v101, v104
	v_max3_f32 v60, v60, v106, v107
	v_max3_f32 v61, v61, v105, v108
	v_max3_f32 v60, v60, v110, v111
	s_nop 0
	v_max3_f32 v61, v61, v109, v81
	v_max3_f32 v60, v60, v80, v82
	v_max3_f32 v61, v61, v83, v84
	v_max3_f32 v60, v60, v86, v87
	v_max3_f32 v61, v61, v85, v88
	v_max3_f32 v60, v60, v90, v91
	v_max3_f32 v61, v61, v89, v92
	v_max3_f32 v60, v60, v94, v95
	v_max3_f32 v60, v60, v93, v61
	v_mov_b32_e32 v61, v60
	s_nop 1
	v_permlane32_swap_b32_e32 v60, v61
	v_max_f32_e32 v60, v60, v61
	v_cmp_lt_f32_e32 vcc, s29, v60
	s_cmp_lg_u64 vcc, 0
	s_cselect_b64 s[44:45], -1, 0
	s_cbranch_vccnz .LBB0_652

.LBB0_647:
	s_add_i32 s44, s68, 0x2000
	s_cmpk_lg_i32 s68, 0x4000
	s_cselect_b32 s60, s44, 0
	s_mov_b64 s[44:45], 0x1490a000
	v_lshl_add_u64 v[78:79], v[186:187], 0, s[44:45]
	s_add_i32 s44, s68, s35
	s_mov_b32 m0, s44
	s_nop 0
	global_load_lds_dwordx4 v[78:79], off
	s_mov_b64 s[44:45], 0x15206000
	v_lshl_add_u64 v[78:79], v[188:189], 0, s[44:45]
	s_add_i32 s44, s60, s49
	s_mov_b32 m0, s44
	s_nop 0
	global_load_lds_dwordx4 v[78:79], off
	v_add_u32_e32 v192, s70, v203
	ds_read_b64_tr_b16 v[148:149], v192 offset:24576
	ds_read_b64_tr_b16 v[150:151], v192 offset:25088
	v_mfma_f32_32x32x16_bf16 v[64:79], v[60:63], v[140:143], v[32:47]
	v_add_f32_e32 v48, v96, v97
	v_add_f32_e32 v48, v98, v48
	v_add_f32_e32 v48, v99, v48
	v_add_f32_e32 v48, v100, v48
	v_add_f32_e32 v48, v101, v48
	v_cvt_pk_bf16_f32 v136, v96, v97
	v_cvt_pk_bf16_f32 v137, v98, v99
	ds_read_b64_tr_b16 v[144:145], v192 offset:28672
	ds_read_b64_tr_b16 v[146:147], v192 offset:29184
	v_add_f32_e32 v48, v102, v48
	v_add_f32_e32 v48, v103, v48
	v_add_f32_e32 v48, v104, v48
	v_add_f32_e32 v116, v105, v48
	v_mfma_f32_32x32x16_bf16 v[48:63], v[172:175], v[140:143], v[32:47]
	v_cvt_pk_bf16_f32 v138, v100, v101
	v_cvt_pk_bf16_f32 v139, v102, v103
	ds_read_b64_tr_b16 v[96:97], v192 offset:25600
	ds_read_b64_tr_b16 v[98:99], v192 offset:26112
	v_mfma_f32_32x32x16_bf16 v[64:79], v[176:179], v[132:135], v[64:79]
	v_add_f32_e32 v100, v106, v116
	v_add_f32_e32 v100, v107, v100
	v_add_f32_e32 v100, v108, v100
	v_add_f32_e32 v116, v109, v100
	v_cvt_pk_bf16_f32 v128, v104, v105
	v_cvt_pk_bf16_f32 v129, v106, v107
	ds_read_b64_tr_b16 v[100:101], v192 offset:29696
	ds_read_b64_tr_b16 v[102:103], v192 offset:30208
	v_mfma_f32_32x32x16_bf16 v[48:63], v[168:171], v[132:135], v[48:63]
	v_add_f32_e32 v104, v110, v116
	v_add_f32_e32 v104, v111, v104
	v_add_f32_e32 v104, v80, v104
	v_add_f32_e32 v116, v81, v104
	v_cvt_pk_bf16_f32 v130, v108, v109
	v_cvt_pk_bf16_f32 v131, v110, v111
	ds_read_b64_tr_b16 v[104:105], v192 offset:26624
	ds_read_b64_tr_b16 v[106:107], v192 offset:27136
	v_mfma_f32_32x32x16_bf16 v[64:79], v[164:167], v[120:123], v[64:79]
	v_add_f32_e32 v108, v82, v116
	v_add_f32_e32 v108, v83, v108
	v_add_f32_e32 v108, v84, v108
	v_add_f32_e32 v108, v85, v108
	v_cvt_pk_bf16_f32 v124, v80, v81
	v_cvt_pk_bf16_f32 v125, v82, v83
	ds_read_b64_tr_b16 v[80:81], v192 offset:30720
	ds_read_b64_tr_b16 v[82:83], v192 offset:31232
	v_mfma_f32_32x32x16_bf16 v[48:63], v[160:163], v[120:123], v[48:63]
	v_add_f32_e32 v108, v86, v108
	v_add_f32_e32 v108, v87, v108
	v_add_f32_e32 v108, v88, v108
	v_add_f32_e32 v108, v89, v108
	v_cvt_pk_bf16_f32 v126, v84, v85
	v_cvt_pk_bf16_f32 v127, v86, v87
	ds_read_b64_tr_b16 v[84:85], v192 offset:27648
	ds_read_b64_tr_b16 v[86:87], v192 offset:28160
	v_mfma_f32_32x32x16_bf16 v[64:79], v[156:159], v[112:115], v[64:79]
	v_add_f32_e32 v108, v90, v108
	v_add_f32_e32 v108, v91, v108
	v_add_f32_e32 v108, v92, v108
	v_add_f32_e32 v108, v93, v108
	v_cvt_pk_bf16_f32 v116, v88, v89
	v_cvt_pk_bf16_f32 v117, v90, v91
	ds_read_b64_tr_b16 v[88:89], v192 offset:31744
	ds_read_b64_tr_b16 v[90:91], v192 offset:32256
	v_mfma_f32_32x32x16_bf16 v[48:63], v[152:155], v[112:115], v[48:63]
	v_add_f32_e32 v108, v94, v108
	v_add_f32_e32 v108, v95, v108
	v_cvt_pk_bf16_f32 v118, v92, v93
	v_cvt_pk_bf16_f32 v119, v94, v95
	v_add_f32_e32 v192, v191, v108
	v_max_f32_e32 v92, v64, v65
	v_max3_f32 v93, v66, v67, v68
	v_max3_f32 v92, v92, v70, v71
	v_max3_f32 v93, v93, v69, v72
	v_max3_f32 v92, v92, v74, v75
	v_max3_f32 v93, v93, v73, v76
	v_max3_f32 v92, v92, v78, v79
	s_nop 0
	v_max3_f32 v93, v93, v77, v49
	v_max3_f32 v92, v92, v48, v50
	v_max3_f32 v93, v93, v51, v52
	v_max3_f32 v92, v92, v54, v55
	v_max3_f32 v93, v93, v53, v56
	v_max3_f32 v92, v92, v58, v59
	v_max3_f32 v93, v93, v57, v60
	v_max3_f32 v92, v92, v62, v63
	v_max3_f32 v92, v92, v61, v93
	v_mov_b32_e32 v93, v92
	s_nop 1
	v_permlane32_swap_b32_e32 v92, v93
	v_max_f32_e32 v92, v92, v93
	v_cmp_lt_f32_e32 vcc, s29, v92
	s_cmp_lg_u64 vcc, 0
	s_cselect_b64 s[44:45], -1, 0
	s_cbranch_vccnz .LBB0_655

.LBB0_721:
	s_movk_i32 s42, 0xe000
	s_mov_b32 s43, -1
	v_lshl_add_u64 v[142:143], v[214:215], 0, s[42:43]
	s_add_i32 s42, s71, s49
	s_mov_b32 m0, s42
	s_nop 0
	global_load_lds_dwordx4 v[142:143], off
	s_movk_i32 s42, 0xbf80
	s_mov_b32 s43, -1
	v_lshl_add_u64 v[142:143], v[212:213], 0, s[42:43]
	s_lshl_b32 s42, s61, 1
	s_add_i32 s44, s42, s60
	s_mov_b32 m0, s44
	s_nop 0
	global_load_lds_dwordx4 v[142:143], off
	s_movk_i32 s42, 0xc000
	s_mov_b32 s43, -1
	v_lshl_add_u64 v[142:143], v[212:213], 0, s[42:43]
	s_add_i32 s42, s44, 0x2000
	s_mov_b32 m0, s42
	s_nop 0
	global_load_lds_dwordx4 v[142:143], off
	v_mfma_f32_32x32x16_bf16 v[128:143], v[204:207], v[172:175], v[64:79]
	v_add_f32_e32 v112, v96, v97
	v_add_f32_e32 v112, v98, v112
	v_add_f32_e32 v112, v99, v112
	v_add_f32_e32 v112, v100, v112
	v_add_f32_e32 v112, v101, v112
	v_cvt_pk_bf16_f32 v160, v96, v97
	v_cvt_pk_bf16_f32 v161, v98, v99
	v_add_f32_e32 v96, v102, v112
	v_mfma_f32_32x32x16_bf16 v[112:127], v[200:203], v[172:175], v[64:79]
	v_add_f32_e32 v96, v103, v96
	v_add_f32_e32 v96, v104, v96
	v_add_f32_e32 v96, v105, v96
	v_cvt_pk_bf16_f32 v162, v100, v101
	v_cvt_pk_bf16_f32 v163, v102, v103
	v_mfma_f32_32x32x16_bf16 v[128:143], v[196:199], v[168:171], v[128:143]
	v_add_f32_e32 v96, v106, v96
	v_add_f32_e32 v96, v107, v96
	v_add_f32_e32 v96, v108, v96
	v_add_f32_e32 v96, v109, v96
	v_cvt_pk_bf16_f32 v152, v104, v105
	v_cvt_pk_bf16_f32 v153, v106, v107
	v_mfma_f32_32x32x16_bf16 v[112:127], v[192:195], v[168:171], v[112:127]
	v_add_f32_e32 v96, v110, v96
	v_add_f32_e32 v96, v111, v96
	v_add_f32_e32 v96, v80, v96
	v_add_f32_e32 v96, v81, v96
	v_cvt_pk_bf16_f32 v154, v108, v109
	v_cvt_pk_bf16_f32 v155, v110, v111
	v_mfma_f32_32x32x16_bf16 v[128:143], v[188:191], v[164:167], v[128:143]
	v_add_f32_e32 v96, v82, v96
	v_add_f32_e32 v96, v83, v96
	v_add_f32_e32 v96, v84, v96
	v_add_f32_e32 v96, v85, v96
	v_cvt_pk_bf16_f32 v148, v80, v81
	v_cvt_pk_bf16_f32 v149, v82, v83
	v_mfma_f32_32x32x16_bf16 v[112:127], v[184:187], v[164:167], v[112:127]
	v_add_f32_e32 v80, v86, v96
	v_add_f32_e32 v80, v87, v80
	v_add_f32_e32 v80, v88, v80
	v_add_f32_e32 v80, v89, v80
	v_cvt_pk_bf16_f32 v150, v84, v85
	v_cvt_pk_bf16_f32 v151, v86, v87
	v_mfma_f32_32x32x16_bf16 v[128:143], v[180:183], v[156:159], v[128:143]
	v_add_f32_e32 v80, v90, v80
	v_add_f32_e32 v80, v91, v80
	v_add_f32_e32 v80, v92, v80
	v_add_f32_e32 v80, v93, v80
	v_cvt_pk_bf16_f32 v144, v88, v89
	v_cvt_pk_bf16_f32 v145, v90, v91
	v_mfma_f32_32x32x16_bf16 v[112:127], v[176:179], v[156:159], v[112:127]
	v_add_f32_e32 v80, v94, v80
	v_add_f32_e32 v82, v95, v80
	v_cvt_pk_bf16_f32 v146, v92, v93
	v_cvt_pk_bf16_f32 v147, v94, v95
	v_add_f32_e32 v204, v252, v82
	v_max_f32_e32 v80, v128, v129
	v_max3_f32 v81, v130, v131, v132
	v_max3_f32 v80, v80, v134, v135
	v_max3_f32 v81, v81, v133, v136
	v_max3_f32 v80, v80, v138, v139
	v_max3_f32 v81, v81, v137, v140
	v_max3_f32 v80, v80, v142, v143
	s_nop 0
	v_max3_f32 v81, v81, v141, v113
	v_max3_f32 v80, v80, v112, v114
	v_max3_f32 v81, v81, v115, v116
	v_max3_f32 v80, v80, v118, v119
	v_max3_f32 v81, v81, v117, v120
	v_max3_f32 v80, v80, v122, v123
	v_max3_f32 v81, v81, v121, v124
	v_max3_f32 v80, v80, v126, v127
	v_max3_f32 v80, v80, v125, v81
	v_mov_b32_e32 v81, v80
	s_nop 1
	v_permlane32_swap_b32_e32 v80, v81
	v_max_f32_e32 v80, v80, v81
	v_cmp_lt_f32_e32 vcc, s29, v80
	s_cmp_lg_u64 vcc, 0
	s_cselect_b64 s[42:43], -1, 0
	s_cbranch_vccnz .LBB0_729

.LBB0_724:
	s_add_i32 s42, s61, 0x2000
	s_cmpk_lg_i32 s61, 0x4000
	s_cselect_b32 s65, s42, 0
	s_add_i32 s42, s61, s49
	s_mov_b32 m0, s42
	s_nop 0
	global_load_lds_dwordx4 v[214:215], off
	s_movk_i32 s42, 0xff80
	s_mov_b32 s43, -1
	v_lshl_add_u64 v[110:111], v[212:213], 0, s[42:43]
	s_lshl_b32 s42, s65, 1
	s_add_i32 s42, s42, s60
	s_mov_b32 m0, s42
	s_nop 0
	global_load_lds_dwordx4 v[110:111], off
	s_addk_i32 s42, 0x2000
	s_mov_b32 m0, s42
	s_nop 0
	global_load_lds_dwordx4 v[212:213], off
	v_mfma_f32_32x32x16_bf16 v[96:111], v[80:83], v[172:175], v[64:79]
	v_add_f32_e32 v84, v128, v129
	v_add_f32_e32 v84, v130, v84
	v_add_f32_e32 v84, v131, v84
	v_add_f32_e32 v84, v132, v84
	v_add_f32_e32 v84, v133, v84
	v_cvt_pk_bf16_f32 v160, v128, v129
	v_cvt_pk_bf16_f32 v161, v130, v131
	v_add_f32_e32 v80, v134, v84
	v_add_f32_e32 v80, v135, v80
	v_add_f32_e32 v80, v136, v80
	v_add_f32_e32 v128, v137, v80
	v_mfma_f32_32x32x16_bf16 v[80:95], v[196:199], v[172:175], v[64:79]
	v_cvt_pk_bf16_f32 v162, v132, v133
	v_cvt_pk_bf16_f32 v163, v134, v135
	v_mfma_f32_32x32x16_bf16 v[96:111], v[200:203], v[168:171], v[96:111]
	v_add_f32_e32 v128, v138, v128
	v_add_f32_e32 v128, v139, v128
	v_add_f32_e32 v128, v140, v128
	v_add_f32_e32 v128, v141, v128
	v_cvt_pk_bf16_f32 v152, v136, v137
	v_cvt_pk_bf16_f32 v153, v138, v139
	v_mfma_f32_32x32x16_bf16 v[80:95], v[192:195], v[168:171], v[80:95]
	v_add_f32_e32 v128, v142, v128
	v_add_f32_e32 v128, v143, v128
	v_add_f32_e32 v128, v112, v128
	v_add_f32_e32 v128, v113, v128
	v_cvt_pk_bf16_f32 v154, v140, v141
	v_cvt_pk_bf16_f32 v155, v142, v143
	v_mfma_f32_32x32x16_bf16 v[96:111], v[188:191], v[164:167], v[96:111]
	v_add_f32_e32 v128, v114, v128
	v_add_f32_e32 v128, v115, v128
	v_add_f32_e32 v128, v116, v128
	v_add_f32_e32 v128, v117, v128
	v_cvt_pk_bf16_f32 v148, v112, v113
	v_cvt_pk_bf16_f32 v149, v114, v115
	v_mfma_f32_32x32x16_bf16 v[80:95], v[184:187], v[164:167], v[80:95]
	v_add_f32_e32 v112, v118, v128
	v_add_f32_e32 v112, v119, v112
	v_add_f32_e32 v112, v120, v112
	v_add_f32_e32 v112, v121, v112
	v_cvt_pk_bf16_f32 v150, v116, v117
	v_cvt_pk_bf16_f32 v151, v118, v119
	v_mfma_f32_32x32x16_bf16 v[96:111], v[180:183], v[156:159], v[96:111]
	v_add_f32_e32 v112, v122, v112
	v_add_f32_e32 v112, v123, v112
	v_add_f32_e32 v112, v124, v112
	v_add_f32_e32 v112, v125, v112
	v_cvt_pk_bf16_f32 v144, v120, v121
	v_cvt_pk_bf16_f32 v145, v122, v123
	v_mfma_f32_32x32x16_bf16 v[80:95], v[176:179], v[156:159], v[80:95]
	v_add_f32_e32 v112, v126, v112
	v_add_f32_e32 v114, v127, v112
	v_cvt_pk_bf16_f32 v146, v124, v125
	v_cvt_pk_bf16_f32 v147, v126, v127
	v_add_f32_e32 v252, v204, v114
	v_max_f32_e32 v112, v96, v97
	v_max3_f32 v113, v98, v99, v100
	v_max3_f32 v112, v112, v102, v103
	v_max3_f32 v113, v113, v101, v104
	v_max3_f32 v112, v112, v106, v107
	v_max3_f32 v113, v113, v105, v108
	v_max3_f32 v112, v112, v110, v111
	s_nop 0
	v_max3_f32 v113, v113, v109, v81
	v_max3_f32 v112, v112, v80, v82
	v_max3_f32 v113, v113, v83, v84
	v_max3_f32 v112, v112, v86, v87
	v_max3_f32 v113, v113, v85, v88
	v_max3_f32 v112, v112, v90, v91
	v_max3_f32 v113, v113, v89, v92
	v_max3_f32 v112, v112, v94, v95
	v_max3_f32 v112, v112, v93, v113
	v_mov_b32_e32 v113, v112
	s_nop 1
	v_permlane32_swap_b32_e32 v112, v113
	v_max_f32_e32 v112, v112, v113
	v_cmp_lt_f32_e32 vcc, s29, v112
	s_cmp_lg_u64 vcc, 0
	s_cselect_b64 s[42:43], -1, 0
	s_cbranch_vccnz .LBB0_732
